# phase-7 V-transpose: third tile moved to blocks 240-255 (off the blocks with an extra rows iteration)
# speedup vs baseline: 1.0143x; 1.0031x over previous
; #define LAS __attribute__((address_space(3)))
; __device__ __forceinline__ void mlapost_tile(ArgP a, int l, int tl, LAS unsigned char* lds, int tid, int wave, int lane, int pm) {
;     const TileGeo g = tile_geo(tl);
;     const bf16_t* KVR = (const bf16_t*)(a->ws + OFF_KVRAW);
;     { u32x4 uv[6];
; #pragma unroll
;       for (int k = 0; k < 6; ++k) { const int idx = tid + k * NTHR, tok = idx / 48, ch = idx % 48; uv[k] = *(const u32x4*)(KVR + (size_t)(g.R0 + tok) * 768 + (ch >> 3) * 128 + 64 + (ch & 7) * 8); }
; #pragma unroll
;       for (int k = 0; k < 6; ++k) { const int idx = tid + k * NTHR, tok = idx / 48, ch = idx % 48; *(LAS u32x4*)(lds + tok * MVT_STR + ch * 16) = uv[k]; } }
; __global__ void __launch_bounds__(NTHR) fwd_megakernel(Args a_unused) {
;     ...
;                 if (pm & 2) for (int tl = bid; tl < 528; tl += G) mlapost_tile(a, l, tl, lds, tid, wave, lane, pm);
.LBB0_748:
	s_mov_b32 s12, s89
	s_cmpk_lg_i32 s90, 0x100
	s_cbranch_scc1 .Ltile7_noremap
	s_add_i32 s12, s12, 16
	s_and_b32 s12, s12, 0xff
.Ltile7_noremap:
	s_cmpk_gt_i32 s12, 0x20f
	s_cbranch_scc1 .LBB0_758
	v_readlane_b32 s0, v254, 48
	v_mov_b32_e32 v15, v0
	v_lshl_add_u32 v19, s0, 6, v1
	s_mov_b32 s0, 0x2aaaaaab
	v_mul_hi_i32 v2, v19, s0
	v_lshrrev_b32_e32 v3, 31, v2
	v_ashrrev_i32_e32 v2, 3, v2
	v_add_u32_e32 v17, v2, v3
	v_mul_lo_u32 v2, v17, 48
	v_sub_u32_e32 v4, v19, v2
	v_lshlrev_b32_e32 v21, 4, v4
	v_lshlrev_b32_e32 v4, 3, v4
	v_and_b32_e32 v18, 56, v4
	v_add_u32_e32 v4, 0x200, v19
	v_mul_hi_i32 v5, v4, s0
	v_lshrrev_b32_e32 v6, 31, v5
	v_ashrrev_i32_e32 v5, 3, v5
	v_add_u32_e32 v32, v5, v6
	v_mul_lo_u32 v5, v32, 48
	v_sub_u32_e32 v6, v4, v5
	v_lshlrev_b32_e32 v23, 4, v6
	v_lshlrev_b32_e32 v6, 3, v6
	v_and_b32_e32 v20, 56, v6
	v_add_u32_e32 v6, 0x400, v19
	v_mul_hi_i32 v7, v6, s0
	v_lshrrev_b32_e32 v8, 31, v7
	v_ashrrev_i32_e32 v7, 3, v7
	v_add_u32_e32 v33, v7, v8
	v_mul_lo_u32 v7, v33, 48
	v_sub_u32_e32 v8, v6, v7
	v_lshlrev_b32_e32 v25, 4, v8
	v_lshlrev_b32_e32 v8, 3, v8
	v_and_b32_e32 v22, 56, v8
	v_add_u32_e32 v8, 0x600, v19
	v_mul_hi_i32 v9, v8, s0
	v_lshrrev_b32_e32 v10, 31, v9
	v_ashrrev_i32_e32 v9, 3, v9
	v_add_u32_e32 v34, v9, v10
	v_mul_lo_u32 v9, v34, 48
	v_sub_u32_e32 v10, v8, v9
	v_lshlrev_b32_e32 v27, 4, v10
	v_lshlrev_b32_e32 v10, 3, v10
	v_and_b32_e32 v24, 56, v10
	v_add_u32_e32 v10, 0x800, v19
	v_mul_hi_i32 v11, v10, s0
	v_lshrrev_b32_e32 v12, 31, v11
	v_ashrrev_i32_e32 v11, 3, v11
	v_add_u32_e32 v35, v11, v12
	v_mul_lo_u32 v11, v35, 48
	v_sub_u32_e32 v12, v10, v11
	v_lshlrev_b32_e32 v29, 4, v12
	v_lshlrev_b32_e32 v12, 3, v12
	v_and_b32_e32 v26, 56, v12
	v_add_u32_e32 v12, 0xa00, v19
	v_mul_hi_i32 v13, v12, s0
	v_lshrrev_b32_e32 v14, 31, v13
	v_ashrrev_i32_e32 v13, 3, v13
	v_add_u32_e32 v36, v13, v14
	v_mul_lo_u32 v13, v36, 48
	v_sub_u32_e32 v14, v12, v13
	v_lshlrev_b32_e32 v30, 4, v14
	v_lshlrev_b32_e32 v14, 3, v14
	s_movk_i32 s0, 0x310
	v_and_b32_e32 v28, 56, v14
	v_mul_lo_u32 v14, v17, s0
	v_add_u32_e32 v31, 0, v14
	v_mul_lo_u32 v14, v32, s0
	v_add_u32_e32 v40, 0, v14
	v_mul_lo_u32 v14, v33, s0
	v_add_u32_e32 v41, 0, v14
	v_mul_lo_u32 v14, v34, s0
	v_add_u32_e32 v42, 0, v14
	v_mul_lo_u32 v14, v35, s0
	v_add_u32_e32 v43, 0, v14
	v_mul_lo_u32 v14, v36, s0
	v_add_u32_e32 v44, 0, v14
	v_lshlrev_b32_e32 v14, 5, v1
	v_and_b32_e32 v38, 32, v14
	v_and_b32_e32 v2, 0xffffff80, v21
	v_and_b32_e32 v4, 0xffffff80, v23
	v_and_b32_e32 v6, 0xffffff80, v25
	v_and_b32_e32 v8, 0xffffff80, v27
	v_and_b32_e32 v10, 0xffffff80, v29
	v_and_b32_e32 v12, 0xffffff80, v30
	v_ashrrev_i32_e32 v37, 1, v19
	s_movk_i32 s0, 0x180
	v_lshlrev_b32_e32 v14, 1, v38
	v_ashrrev_i32_e32 v3, 31, v2
	v_ashrrev_i32_e32 v5, 31, v4
	v_ashrrev_i32_e32 v7, 31, v6
	v_ashrrev_i32_e32 v9, 31, v8
	v_ashrrev_i32_e32 v11, 31, v10
	v_ashrrev_i32_e32 v13, 31, v12
	v_cmp_gt_i32_e64 s[38:39], s0, v37
	v_lshl_add_u64 v[14:15], s[10:11], 0, v[14:15]
	s_mov_b64 s[0:1], 0x1bdb0000
	v_mul_u32_u24_e32 v38, 0x310, v38
	v_and_b32_e32 v19, -2, v19
	v_lshl_add_u64 v[2:3], v[2:3], 1, s[10:11]
	v_lshl_add_u64 v[4:5], v[4:5], 1, s[10:11]
	v_lshl_add_u64 v[6:7], v[6:7], 1, s[10:11]
	v_lshl_add_u64 v[8:9], v[8:9], 1, s[10:11]
	v_lshl_add_u64 v[10:11], v[10:11], 1, s[10:11]
	v_lshl_add_u64 v[12:13], v[12:13], 1, s[10:11]
	v_lshl_add_u64 v[14:15], v[14:15], 0, s[0:1]
	v_and_b32_e32 v16, 63, v37
	v_add3_u32 v38, v38, v19, 0
	v_lshlrev_b32_e32 v18, 1, v18
	v_lshlrev_b32_e32 v20, 1, v20
	v_lshlrev_b32_e32 v22, 1, v22
	v_lshlrev_b32_e32 v24, 1, v24
	v_lshlrev_b32_e32 v26, 1, v26
	v_lshlrev_b32_e32 v28, 1, v28
	v_add_u32_e32 v39, v31, v21
	v_add_u32_e32 v40, v40, v23
	v_add_u32_e32 v41, v41, v25
	v_add_u32_e32 v42, v42, v27
	v_add_u32_e32 v43, v43, v29
	v_add_u32_e32 v44, v44, v30
	s_branch .LBB0_751
